# prologue: half of the workgroups run their compute-bound S5-table item in the middle of their memory-bound transpose items, so table math overlaps weight streaming
# speedup vs baseline: 1.0162x; 1.0043x over previous
.LBB0_5:
	s_or_b64 exec, exec, s[2:3]
	s_load_dwordx16 s[4:19], s[0:1], 0x0
	s_load_dwordx16 s[48:63], s[0:1], 0x80
	s_cmpk_gt_i32 s20, 0x2dd0
	s_waitcnt lgkmcnt(0)
	v_writelane_b32 v252, s4, 18
	s_nop 1
	v_writelane_b32 v252, s5, 19
	v_writelane_b32 v252, s6, 20
	v_writelane_b32 v252, s7, 21
	v_writelane_b32 v252, s8, 22
	v_writelane_b32 v252, s9, 23
	v_writelane_b32 v252, s10, 24
	v_writelane_b32 v252, s11, 25
	v_writelane_b32 v252, s12, 26
	v_writelane_b32 v252, s13, 27
	v_writelane_b32 v252, s14, 28
	v_writelane_b32 v252, s15, 29
	v_writelane_b32 v252, s16, 30
	v_writelane_b32 v252, s17, 31
	v_writelane_b32 v252, s18, 32
	v_writelane_b32 v252, s19, 33
	s_load_dwordx16 s[4:19], s[0:1], 0x40
	s_waitcnt lgkmcnt(0)
	v_writelane_b32 v252, s4, 34
	s_nop 1
	v_writelane_b32 v252, s5, 35
	v_writelane_b32 v252, s6, 36
	v_writelane_b32 v252, s7, 37
	v_writelane_b32 v252, s8, 38
	v_writelane_b32 v252, s9, 39
	v_writelane_b32 v252, s10, 40
	v_writelane_b32 v252, s11, 41
	v_writelane_b32 v252, s12, 42
	v_writelane_b32 v252, s13, 43
	v_writelane_b32 v252, s14, 44
	v_writelane_b32 v252, s15, 45
	v_writelane_b32 v252, s16, 46
	v_writelane_b32 v252, s17, 47
	v_writelane_b32 v252, s18, 48
	v_writelane_b32 v252, s19, 49
	v_writelane_b32 v252, s28, 50
	s_nop 1
	v_writelane_b32 v252, s29, 51
	v_writelane_b32 v252, s48, 52
	s_nop 1
	v_writelane_b32 v252, s49, 53
	v_writelane_b32 v252, s50, 54
	v_writelane_b32 v252, s51, 55
	v_writelane_b32 v252, s52, 56
	v_writelane_b32 v252, s53, 57
	v_writelane_b32 v252, s54, 58
	v_writelane_b32 v252, s55, 59
	v_writelane_b32 v253, s60, 0
	v_writelane_b32 v252, s56, 60
	v_writelane_b32 v253, s61, 1
	v_writelane_b32 v252, s57, 61
	v_writelane_b32 v253, s62, 2
	v_writelane_b32 v252, s58, 62
	v_writelane_b32 v253, s63, 3
	v_writelane_b32 v252, s59, 63
	v_writelane_b32 v253, s20, 4
	s_cbranch_scc1 .LBB0_88
	v_writelane_b32 v253, s26, 5
	s_add_u32 s0, s94, 0x13500000
	v_writelane_b32 v253, s0, 7
	s_addc_u32 s0, s95, 0
	v_writelane_b32 v253, s0, 8
	s_add_u32 s0, s94, 0x11f00000
	v_writelane_b32 v253, s0, 10
	s_addc_u32 s0, s95, 0
	v_writelane_b32 v253, s0, 11
	s_add_u32 s0, s94, 0xf300000
	v_writelane_b32 v253, s0, 13
	s_addc_u32 s0, s95, 0
	v_writelane_b32 v253, s0, 14
	s_add_u32 s0, s94, 0xeb00000
	v_writelane_b32 v253, s0, 15
	s_addc_u32 s0, s95, 0
	v_writelane_b32 v253, s0, 16
	s_add_u32 s0, s94, 0xe100000
	v_writelane_b32 v253, s0, 17
	s_addc_u32 s0, s95, 0
	v_writelane_b32 v253, s0, 19
	s_add_u32 s0, s94, 0x17a6d600
	s_addc_u32 s1, s95, 0
	s_add_u32 s18, s94, 0x17a68000
	v_writelane_b32 v253, s0, 20
	s_addc_u32 s19, s95, 0
	s_mov_b32 s10, 0x11111111
	v_writelane_b32 v253, s1, 21
	s_add_u32 s0, s94, 0x13580000
	v_writelane_b32 v253, s0, 22
	s_addc_u32 s0, s95, 0
	v_writelane_b32 v253, s0, 24
	s_add_u32 s0, s94, 0x13658000
	v_writelane_b32 v253, s0, 26
	s_addc_u32 s0, s95, 0
	v_writelane_b32 v253, s0, 28
	s_add_u32 s0, s94, 0x13a58000
	v_writelane_b32 v253, s0, 30
	s_addc_u32 s0, s95, 0
	v_writelane_b32 v253, s0, 32
	s_add_u32 s0, s94, 0x15a58000
	v_writelane_b32 v253, s0, 34
	s_addc_u32 s0, s95, 0
	v_writelane_b32 v253, s0, 36
	s_add_u32 s0, s94, 0x17a58000
	s_addc_u32 s1, s95, 0
	v_writelane_b32 v253, s0, 38
	s_mov_b32 s30, 0x652b82fe
	s_mov_b32 s22, 0xfefa39ef
	v_writelane_b32 v253, s1, 39
	s_add_i32 s0, 0, 0xa200
	v_writelane_b32 v253, s0, 40
	s_add_i32 s0, 0, 0x8200
	s_mov_b32 s24, 0x3b39803f
	s_mov_b32 s26, 0x6a5dcb37
	s_mov_b32 s11, 0x3f811111
	s_mov_b32 s2, 0x6dc9c883
	s_mov_b32 s74, 0x54442d18
	s_mov_b32 s34, 0x33145c07
	s_mov_b32 s48, 0x13a86d09
	s_mov_b32 s52, 0xe733b81f
	s_mov_b32 s42, 0x67f544e4
	s_mov_b32 s56, 0xa556c734
	s_mov_b32 s68, 0x1a01a01a
	s_mov_b32 s60, 0x55555555
	s_mov_b32 s38, 0xeff8d898
	s_mov_b32 s64, 0xa8c07c9d
	s_mov_b32 s66, 0xb7789f5c
	s_mov_b32 s70, 0x16c16c17
	s_mov_b32 s73, 0x3fa55555
	v_writelane_b32 v253, s0, 42
	s_mov_b32 s63, s20
	s_mov_b32 s20, 0xfca7ab0c
	s_mov_b32 s54, 0
	s_mov_b32 s96, 0
	v_mov_b32_e32 v39, 0
	s_mov_b32 s31, 0x3ff71547
	s_mov_b32 s23, 0xbfe62e42
	s_mov_b32 s25, 0xbc7abc9e
	s_mov_b32 s27, 0x3e5ade15
	s_mov_b32 s3, 0x3fe45f30
	s_mov_b32 s75, 0xbff921fb
	s_mov_b32 s35, 0xbc91a626
	s_mov_b32 s49, 0x3de61246
	s_mov_b32 s53, 0xbd6ae7f3
	s_mov_b32 s43, 0xbe5ae645
	s_mov_b32 s57, 0x3ec71de3
	s_mov_b32 s69, 0xbf2a01a0
	s_mov_b32 s61, 0xbfc55555
	s_mov_b32 s39, 0x3e21eed8
	s_mov_b32 s65, 0xbda93974
	s_mov_b32 s67, 0xbe927e4f
	s_mov_b32 s59, 0x3efa01a0
	s_mov_b32 s58, s68
	s_mov_b32 s71, 0xbf56c16c
	s_mov_b32 s72, s60
	s_mov_b32 s28, 0x11122322
	s_mov_b32 s29, s11
	s_mov_b32 s14, 0x555502a1
	s_mov_b32 s15, s73
	v_mov_b32_e32 v40, 0xfca7ab0c
	v_mov_b32_e32 v41, 0x3e928af3
	v_mov_b32_e32 v42, 0x623fde64
	v_mov_b32_e32 v43, 0x3ec71dee
	v_mov_b32_e32 v44, 0x7c89e6b0
	v_mov_b32_e32 v45, 0x3efa0199
	v_mov_b32_e32 v46, 0x14761f6e
	v_mov_b32_e32 v47, 0x3f2a01a0
	v_mov_b32_e32 v48, 0x1852b7b0
	v_mov_b32_e32 v49, 0x3f56c16c
	v_mov_b32_e32 v50, 0x11122322
	v_mov_b32_e32 v51, 0x3f811111
	v_mov_b32_e32 v52, 0x555502a1
	v_mov_b32_e32 v53, 0x3fa55555
	v_mov_b32_e32 v54, 0x55555511
	v_mov_b32_e32 v55, 0x3fc55555
	v_mov_b32_e32 v56, 11
	v_mov_b32_e32 v57, 0x3fe00000
	v_mov_b32_e32 v88, 0x7ff00000
	v_mov_b32_e32 v58, 0x13a86d09
	v_mov_b32_e32 v59, 0x3de61246
	v_mov_b32_e32 v60, 0x67f544e4
	v_mov_b32_e32 v61, 0xbe5ae645
	v_mov_b32_e32 v62, 0xa556c734
	v_mov_b32_e32 v63, 0x3ec71de3
	v_mov_b32_e32 v64, 0x1a01a01a
	v_mov_b32_e32 v65, 0xbf2a01a0
	v_mov_b32_e32 v66, 0x11111111
	v_mov_b32_e32 v68, 0x55555555
	v_mov_b32_e32 v69, 0xbfc55555
	v_mov_b32_e32 v70, 0xeff8d898
	v_mov_b32_e32 v71, 0x3e21eed8
	v_mov_b32_e32 v72, 0xb7789f5c
	v_mov_b32_e32 v73, 0xbe927e4f
	v_mov_b32_e32 v75, 0x3efa01a0
	v_mov_b32_e32 v76, 0x16c16c17
	v_mov_b32_e32 v77, 0xbf56c16c
	v_mov_b32_e32 v89, 0x1800000
	v_mov_b32_e32 v90, 1
	s_movk_i32 s33, 0x7fff
	s_movk_i32 s16, 0x6000
	s_mov_b32 s62, 0x20000
	s_mov_b32 s21, 0x3e928af3
	s_mov_b32 s98, 0
	s_cmpk_lt_u32 s63, 0x100
	s_cbranch_scc1 .Lpro_norm
	v_readlane_b32 s99, v252, 50
	s_nop 3
	s_cmpk_lg_i32 s99, 0x200
	s_cbranch_scc1 .Lpro_norm
	s_mov_b32 s98, 1
	s_addk_i32 s63, 0x200
.Lpro_norm:
	v_writelane_b32 v253, s63, 43
	s_mov_b32 s17, 0
	s_mov_b32 s55, 0x40900000
	s_mov_b32 s97, 0xc090cc00
	s_branch .LBB0_9

.LBB0_8:
	v_readlane_b32 s0, v252, 50
	v_readlane_b32 s1, v252, 51
	v_readlane_b32 s1, v253, 43
	s_add_i32 s63, s63, s0
	s_add_i32 s1, s1, s0
	v_writelane_b32 v253, s1, 43
	s_cmp_eq_u32 s98, 2
	s_cbranch_scc0 .Lpro_chk1
	s_mov_b32 s63, s99
	s_mov_b32 s98, 0
	s_nop 0
	v_writelane_b32 v253, s63, 43
	s_branch .Lpro_cont
.Lpro_chk1:
	s_cmp_eq_u32 s98, 1
	s_cbranch_scc0 .Lpro_cont
	s_cmpk_lt_i32 s63, 0x1600
	s_cbranch_scc1 .Lpro_cont
	s_mov_b32 s99, s63
	s_mov_b32 s98, 2
	v_readlane_b32 s63, v253, 4
	s_nop 1
	v_writelane_b32 v253, s63, 43
.Lpro_cont:
	s_cmpk_lt_i32 s63, 0x2dd1
	s_barrier
	s_cbranch_scc0 .LBB0_87
